# adds: adaLN GEMV k-loop double-buffered (16 row loads in flight, scalar row pointer) + counted lgkmcnt in indexer MFMA block
# baseline (speedup 1.0000x reference)
.LBB0_47:
	s_mul_hi_i32 s4, s22, 0x2aaaaaab
	s_lshr_b32 s6, s4, 31
	s_ashr_i32 s4, s4, 4
	s_add_i32 s4, s4, s6
	s_mul_i32 s6, s4, 0x60
	s_sub_i32 s6, s22, s6
	v_lshl_or_b32 v16, s6, 7, v32
	s_lshl_b32 s6, s4, 8
	s_mul_i32 s7, s4, 0xc00000
	s_mul_hi_i32 s10, s6, 0xc000
	s_add_u32 s6, s40, s7
	s_addc_u32 s7, s41, s10
	v_ashrrev_i32_e32 v17, 31, v16
	v_lshl_add_u64 v[18:19], v[16:17], 2, s[6:7]
	s_mov_b64 s[28:29], s[6:7]
	s_lshl_b32 s6, s4, 10
	v_mov_b32_e32 v24, 0
	s_add_i32 s10, s6, 0
	s_mov_b64 s[6:7], 0
	v_mov_b32_e32 v25, v24
	v_mov_b32_e32 v26, v24
	v_mov_b32_e32 v27, v24
	v_mov_b32_e32 v22, v24
	v_mov_b32_e32 v23, v24
	v_mov_b32_e32 v20, v24
	v_mov_b32_e32 v21, v24
.LBB0_48:
	v_lshlrev_b32_e32 v124, 2, v16
	s_mov_b32 s24, 15
	global_load_dwordx2 v[78:79], v124, s[28:29] nt
	s_add_u32 s28, s28, 0xc000
	s_addc_u32 s29, s29, 0
	global_load_dwordx2 v[80:81], v124, s[28:29] nt
	s_add_u32 s28, s28, 0xc000
	s_addc_u32 s29, s29, 0
	global_load_dwordx2 v[82:83], v124, s[28:29] nt
	s_add_u32 s28, s28, 0xc000
	s_addc_u32 s29, s29, 0
	global_load_dwordx2 v[84:85], v124, s[28:29] nt
	s_add_u32 s28, s28, 0xc000
	s_addc_u32 s29, s29, 0
	global_load_dwordx2 v[86:87], v124, s[28:29] nt
	s_add_u32 s28, s28, 0xc000
	s_addc_u32 s29, s29, 0
	global_load_dwordx2 v[88:89], v124, s[28:29] nt
	s_add_u32 s28, s28, 0xc000
	s_addc_u32 s29, s29, 0
	global_load_dwordx2 v[90:91], v124, s[28:29] nt
	s_add_u32 s28, s28, 0xc000
	s_addc_u32 s29, s29, 0
	global_load_dwordx2 v[92:93], v124, s[28:29] nt
	s_add_u32 s28, s28, 0xc000
	s_addc_u32 s29, s29, 0
.Lada_loop:
	global_load_dwordx2 v[108:109], v124, s[28:29] nt
	s_add_u32 s28, s28, 0xc000
	s_addc_u32 s29, s29, 0
	global_load_dwordx2 v[110:111], v124, s[28:29] nt
	s_add_u32 s28, s28, 0xc000
	s_addc_u32 s29, s29, 0
	global_load_dwordx2 v[112:113], v124, s[28:29] nt
	s_add_u32 s28, s28, 0xc000
	s_addc_u32 s29, s29, 0
	global_load_dwordx2 v[114:115], v124, s[28:29] nt
	s_add_u32 s28, s28, 0xc000
	s_addc_u32 s29, s29, 0
	global_load_dwordx2 v[116:117], v124, s[28:29] nt
	s_add_u32 s28, s28, 0xc000
	s_addc_u32 s29, s29, 0
	global_load_dwordx2 v[118:119], v124, s[28:29] nt
	s_add_u32 s28, s28, 0xc000
	s_addc_u32 s29, s29, 0
	global_load_dwordx2 v[120:121], v124, s[28:29] nt
	s_add_u32 s28, s28, 0xc000
	s_addc_u32 s29, s29, 0
	global_load_dwordx2 v[122:123], v124, s[28:29] nt
	s_add_u32 s28, s28, 0xc000
	s_addc_u32 s29, s29, 0
	v_mov_b32_e32 v0, s10
	ds_read_b128 v[28:31], v0
	ds_read_b128 v[50:53], v0 offset:16
	ds_read_b128 v[54:57], v0 offset:16384
	ds_read_b128 v[58:61], v0 offset:16400
	ds_read_b128 v[62:65], v0 offset:32768
	ds_read_b128 v[66:69], v0 offset:32784
	ds_read_b128 v[70:73], v0 offset:49152
	ds_read_b128 v[74:77], v0 offset:49168
	s_waitcnt lgkmcnt(7)
	v_mov_b32_e32 v0, v31
	s_waitcnt lgkmcnt(5)
	v_mov_b32_e32 v94, v57
	s_waitcnt lgkmcnt(3)
	v_mov_b32_e32 v96, v65
	s_waitcnt lgkmcnt(1)
	v_mov_b32_e32 v98, v73
	v_mov_b32_e32 v100, v53
	v_mov_b32_e32 v102, v61
	v_mov_b32_e32 v104, v69
	s_waitcnt lgkmcnt(0)
	v_mov_b32_e32 v106, v77
	s_waitcnt vmcnt(15)
	v_pk_fma_f32 v[24:25], v[78:79], v[28:29], v[24:25] op_sel_hi:[1,0,1]
	v_pk_fma_f32 v[26:27], v[78:79], v[54:55], v[26:27] op_sel_hi:[1,0,1]
	v_pk_fma_f32 v[22:23], v[78:79], v[62:63], v[22:23] op_sel_hi:[1,0,1]
	v_pk_fma_f32 v[20:21], v[78:79], v[70:71], v[20:21] op_sel_hi:[1,0,1]
	s_waitcnt vmcnt(14)
	v_pk_fma_f32 v[24:25], v[80:81], v[28:29], v[24:25] op_sel:[0,1,0]
	v_pk_fma_f32 v[26:27], v[80:81], v[54:55], v[26:27] op_sel:[0,1,0]
	v_pk_fma_f32 v[22:23], v[80:81], v[62:63], v[22:23] op_sel:[0,1,0]
	v_pk_fma_f32 v[20:21], v[80:81], v[70:71], v[20:21] op_sel:[0,1,0]
	s_waitcnt vmcnt(13)
	v_pk_fma_f32 v[24:25], v[82:83], v[30:31], v[24:25] op_sel_hi:[1,0,1]
	v_pk_fma_f32 v[26:27], v[82:83], v[56:57], v[26:27] op_sel_hi:[1,0,1]
	v_pk_fma_f32 v[22:23], v[82:83], v[64:65], v[22:23] op_sel_hi:[1,0,1]
	v_pk_fma_f32 v[20:21], v[82:83], v[72:73], v[20:21] op_sel_hi:[1,0,1]
	s_waitcnt vmcnt(12)
	v_pk_fma_f32 v[24:25], v[84:85], v[0:1], v[24:25] op_sel_hi:[1,0,1]
	v_pk_fma_f32 v[26:27], v[84:85], v[94:95], v[26:27] op_sel_hi:[1,0,1]
	v_pk_fma_f32 v[22:23], v[84:85], v[96:97], v[22:23] op_sel_hi:[1,0,1]
	v_pk_fma_f32 v[20:21], v[84:85], v[98:99], v[20:21] op_sel_hi:[1,0,1]
	s_waitcnt vmcnt(11)
	v_pk_fma_f32 v[24:25], v[86:87], v[50:51], v[24:25] op_sel_hi:[1,0,1]
	v_pk_fma_f32 v[26:27], v[86:87], v[58:59], v[26:27] op_sel_hi:[1,0,1]
	v_pk_fma_f32 v[22:23], v[86:87], v[66:67], v[22:23] op_sel_hi:[1,0,1]
	v_pk_fma_f32 v[20:21], v[86:87], v[74:75], v[20:21] op_sel_hi:[1,0,1]
	s_waitcnt vmcnt(10)
	v_pk_fma_f32 v[24:25], v[88:89], v[50:51], v[24:25] op_sel:[0,1,0]
	v_pk_fma_f32 v[26:27], v[88:89], v[58:59], v[26:27] op_sel:[0,1,0]
	v_pk_fma_f32 v[22:23], v[88:89], v[66:67], v[22:23] op_sel:[0,1,0]
	v_pk_fma_f32 v[20:21], v[88:89], v[74:75], v[20:21] op_sel:[0,1,0]
	s_waitcnt vmcnt(9)
	v_pk_fma_f32 v[24:25], v[90:91], v[52:53], v[24:25] op_sel_hi:[1,0,1]
	v_pk_fma_f32 v[26:27], v[90:91], v[60:61], v[26:27] op_sel_hi:[1,0,1]
	v_pk_fma_f32 v[22:23], v[90:91], v[68:69], v[22:23] op_sel_hi:[1,0,1]
	v_pk_fma_f32 v[20:21], v[90:91], v[76:77], v[20:21] op_sel_hi:[1,0,1]
	s_waitcnt vmcnt(8)
	v_pk_fma_f32 v[24:25], v[92:93], v[100:101], v[24:25] op_sel_hi:[1,0,1]
	v_pk_fma_f32 v[26:27], v[92:93], v[102:103], v[26:27] op_sel_hi:[1,0,1]
	v_pk_fma_f32 v[22:23], v[92:93], v[104:105], v[22:23] op_sel_hi:[1,0,1]
	v_pk_fma_f32 v[20:21], v[92:93], v[106:107], v[20:21] op_sel_hi:[1,0,1]
	s_add_i32 s10, s10, 32
	global_load_dwordx2 v[78:79], v124, s[28:29] nt
	s_add_u32 s28, s28, 0xc000
	s_addc_u32 s29, s29, 0
	global_load_dwordx2 v[80:81], v124, s[28:29] nt
	s_add_u32 s28, s28, 0xc000
	s_addc_u32 s29, s29, 0
	global_load_dwordx2 v[82:83], v124, s[28:29] nt
	s_add_u32 s28, s28, 0xc000
	s_addc_u32 s29, s29, 0
	global_load_dwordx2 v[84:85], v124, s[28:29] nt
	s_add_u32 s28, s28, 0xc000
	s_addc_u32 s29, s29, 0
	global_load_dwordx2 v[86:87], v124, s[28:29] nt
	s_add_u32 s28, s28, 0xc000
	s_addc_u32 s29, s29, 0
	global_load_dwordx2 v[88:89], v124, s[28:29] nt
	s_add_u32 s28, s28, 0xc000
	s_addc_u32 s29, s29, 0
	global_load_dwordx2 v[90:91], v124, s[28:29] nt
	s_add_u32 s28, s28, 0xc000
	s_addc_u32 s29, s29, 0
	global_load_dwordx2 v[92:93], v124, s[28:29] nt
	s_add_u32 s28, s28, 0xc000
	s_addc_u32 s29, s29, 0
	v_mov_b32_e32 v0, s10
	ds_read_b128 v[28:31], v0
	ds_read_b128 v[50:53], v0 offset:16
	ds_read_b128 v[54:57], v0 offset:16384
	ds_read_b128 v[58:61], v0 offset:16400
	ds_read_b128 v[62:65], v0 offset:32768
	ds_read_b128 v[66:69], v0 offset:32784
	ds_read_b128 v[70:73], v0 offset:49152
	ds_read_b128 v[74:77], v0 offset:49168
	s_waitcnt lgkmcnt(7)
	v_mov_b32_e32 v0, v31
	s_waitcnt lgkmcnt(5)
	v_mov_b32_e32 v94, v57
	s_waitcnt lgkmcnt(3)
	v_mov_b32_e32 v96, v65
	s_waitcnt lgkmcnt(1)
	v_mov_b32_e32 v98, v73
	v_mov_b32_e32 v100, v53
	v_mov_b32_e32 v102, v61
	v_mov_b32_e32 v104, v69
	s_waitcnt lgkmcnt(0)
	v_mov_b32_e32 v106, v77
	s_waitcnt vmcnt(15)
	v_pk_fma_f32 v[24:25], v[108:109], v[28:29], v[24:25] op_sel_hi:[1,0,1]
	v_pk_fma_f32 v[26:27], v[108:109], v[54:55], v[26:27] op_sel_hi:[1,0,1]
	v_pk_fma_f32 v[22:23], v[108:109], v[62:63], v[22:23] op_sel_hi:[1,0,1]
	v_pk_fma_f32 v[20:21], v[108:109], v[70:71], v[20:21] op_sel_hi:[1,0,1]
	s_waitcnt vmcnt(14)
	v_pk_fma_f32 v[24:25], v[110:111], v[28:29], v[24:25] op_sel:[0,1,0]
	v_pk_fma_f32 v[26:27], v[110:111], v[54:55], v[26:27] op_sel:[0,1,0]
	v_pk_fma_f32 v[22:23], v[110:111], v[62:63], v[22:23] op_sel:[0,1,0]
	v_pk_fma_f32 v[20:21], v[110:111], v[70:71], v[20:21] op_sel:[0,1,0]
	s_waitcnt vmcnt(13)
	v_pk_fma_f32 v[24:25], v[112:113], v[30:31], v[24:25] op_sel_hi:[1,0,1]
	v_pk_fma_f32 v[26:27], v[112:113], v[56:57], v[26:27] op_sel_hi:[1,0,1]
	v_pk_fma_f32 v[22:23], v[112:113], v[64:65], v[22:23] op_sel_hi:[1,0,1]
	v_pk_fma_f32 v[20:21], v[112:113], v[72:73], v[20:21] op_sel_hi:[1,0,1]
	s_waitcnt vmcnt(12)
	v_pk_fma_f32 v[24:25], v[114:115], v[0:1], v[24:25] op_sel_hi:[1,0,1]
	v_pk_fma_f32 v[26:27], v[114:115], v[94:95], v[26:27] op_sel_hi:[1,0,1]
	v_pk_fma_f32 v[22:23], v[114:115], v[96:97], v[22:23] op_sel_hi:[1,0,1]
	v_pk_fma_f32 v[20:21], v[114:115], v[98:99], v[20:21] op_sel_hi:[1,0,1]
	s_waitcnt vmcnt(11)
	v_pk_fma_f32 v[24:25], v[116:117], v[50:51], v[24:25] op_sel_hi:[1,0,1]
	v_pk_fma_f32 v[26:27], v[116:117], v[58:59], v[26:27] op_sel_hi:[1,0,1]
	v_pk_fma_f32 v[22:23], v[116:117], v[66:67], v[22:23] op_sel_hi:[1,0,1]
	v_pk_fma_f32 v[20:21], v[116:117], v[74:75], v[20:21] op_sel_hi:[1,0,1]
	s_waitcnt vmcnt(10)
	v_pk_fma_f32 v[24:25], v[118:119], v[50:51], v[24:25] op_sel:[0,1,0]
	v_pk_fma_f32 v[26:27], v[118:119], v[58:59], v[26:27] op_sel:[0,1,0]
	v_pk_fma_f32 v[22:23], v[118:119], v[66:67], v[22:23] op_sel:[0,1,0]
	v_pk_fma_f32 v[20:21], v[118:119], v[74:75], v[20:21] op_sel:[0,1,0]
	s_waitcnt vmcnt(9)
	v_pk_fma_f32 v[24:25], v[120:121], v[52:53], v[24:25] op_sel_hi:[1,0,1]
	v_pk_fma_f32 v[26:27], v[120:121], v[60:61], v[26:27] op_sel_hi:[1,0,1]
	v_pk_fma_f32 v[22:23], v[120:121], v[68:69], v[22:23] op_sel_hi:[1,0,1]
	v_pk_fma_f32 v[20:21], v[120:121], v[76:77], v[20:21] op_sel_hi:[1,0,1]
	s_waitcnt vmcnt(8)
	v_pk_fma_f32 v[24:25], v[122:123], v[100:101], v[24:25] op_sel_hi:[1,0,1]
	v_pk_fma_f32 v[26:27], v[122:123], v[102:103], v[26:27] op_sel_hi:[1,0,1]
	v_pk_fma_f32 v[22:23], v[122:123], v[104:105], v[22:23] op_sel_hi:[1,0,1]
	v_pk_fma_f32 v[20:21], v[122:123], v[106:107], v[20:21] op_sel_hi:[1,0,1]
	s_add_i32 s10, s10, 32
	s_sub_u32 s24, s24, 1
	s_cmp_lg_u32 s24, 0
	s_cbranch_scc1 .Lada_loop
	global_load_dwordx2 v[108:109], v124, s[28:29] nt
	s_add_u32 s28, s28, 0xc000
	s_addc_u32 s29, s29, 0
	global_load_dwordx2 v[110:111], v124, s[28:29] nt
	s_add_u32 s28, s28, 0xc000
	s_addc_u32 s29, s29, 0
	global_load_dwordx2 v[112:113], v124, s[28:29] nt
	s_add_u32 s28, s28, 0xc000
	s_addc_u32 s29, s29, 0
	global_load_dwordx2 v[114:115], v124, s[28:29] nt
	s_add_u32 s28, s28, 0xc000
	s_addc_u32 s29, s29, 0
	global_load_dwordx2 v[116:117], v124, s[28:29] nt
	s_add_u32 s28, s28, 0xc000
	s_addc_u32 s29, s29, 0
	global_load_dwordx2 v[118:119], v124, s[28:29] nt
	s_add_u32 s28, s28, 0xc000
	s_addc_u32 s29, s29, 0
	global_load_dwordx2 v[120:121], v124, s[28:29] nt
	s_add_u32 s28, s28, 0xc000
	s_addc_u32 s29, s29, 0
	global_load_dwordx2 v[122:123], v124, s[28:29] nt
	s_add_u32 s28, s28, 0xc000
	s_addc_u32 s29, s29, 0
	v_mov_b32_e32 v0, s10
	ds_read_b128 v[28:31], v0
	ds_read_b128 v[50:53], v0 offset:16
	ds_read_b128 v[54:57], v0 offset:16384
	ds_read_b128 v[58:61], v0 offset:16400
	ds_read_b128 v[62:65], v0 offset:32768
	ds_read_b128 v[66:69], v0 offset:32784
	ds_read_b128 v[70:73], v0 offset:49152
	ds_read_b128 v[74:77], v0 offset:49168
	s_waitcnt lgkmcnt(7)
	v_mov_b32_e32 v0, v31
	s_waitcnt lgkmcnt(5)
	v_mov_b32_e32 v94, v57
	s_waitcnt lgkmcnt(3)
	v_mov_b32_e32 v96, v65
	s_waitcnt lgkmcnt(1)
	v_mov_b32_e32 v98, v73
	v_mov_b32_e32 v100, v53
	v_mov_b32_e32 v102, v61
	v_mov_b32_e32 v104, v69
	s_waitcnt lgkmcnt(0)
	v_mov_b32_e32 v106, v77
	s_waitcnt vmcnt(15)
	v_pk_fma_f32 v[24:25], v[78:79], v[28:29], v[24:25] op_sel_hi:[1,0,1]
	v_pk_fma_f32 v[26:27], v[78:79], v[54:55], v[26:27] op_sel_hi:[1,0,1]
	v_pk_fma_f32 v[22:23], v[78:79], v[62:63], v[22:23] op_sel_hi:[1,0,1]
	v_pk_fma_f32 v[20:21], v[78:79], v[70:71], v[20:21] op_sel_hi:[1,0,1]
	s_waitcnt vmcnt(14)
	v_pk_fma_f32 v[24:25], v[80:81], v[28:29], v[24:25] op_sel:[0,1,0]
	v_pk_fma_f32 v[26:27], v[80:81], v[54:55], v[26:27] op_sel:[0,1,0]
	v_pk_fma_f32 v[22:23], v[80:81], v[62:63], v[22:23] op_sel:[0,1,0]
	v_pk_fma_f32 v[20:21], v[80:81], v[70:71], v[20:21] op_sel:[0,1,0]
	s_waitcnt vmcnt(13)
	v_pk_fma_f32 v[24:25], v[82:83], v[30:31], v[24:25] op_sel_hi:[1,0,1]
	v_pk_fma_f32 v[26:27], v[82:83], v[56:57], v[26:27] op_sel_hi:[1,0,1]
	v_pk_fma_f32 v[22:23], v[82:83], v[64:65], v[22:23] op_sel_hi:[1,0,1]
	v_pk_fma_f32 v[20:21], v[82:83], v[72:73], v[20:21] op_sel_hi:[1,0,1]
	s_waitcnt vmcnt(12)
	v_pk_fma_f32 v[24:25], v[84:85], v[0:1], v[24:25] op_sel_hi:[1,0,1]
	v_pk_fma_f32 v[26:27], v[84:85], v[94:95], v[26:27] op_sel_hi:[1,0,1]
	v_pk_fma_f32 v[22:23], v[84:85], v[96:97], v[22:23] op_sel_hi:[1,0,1]
	v_pk_fma_f32 v[20:21], v[84:85], v[98:99], v[20:21] op_sel_hi:[1,0,1]
	s_waitcnt vmcnt(11)
	v_pk_fma_f32 v[24:25], v[86:87], v[50:51], v[24:25] op_sel_hi:[1,0,1]
	v_pk_fma_f32 v[26:27], v[86:87], v[58:59], v[26:27] op_sel_hi:[1,0,1]
	v_pk_fma_f32 v[22:23], v[86:87], v[66:67], v[22:23] op_sel_hi:[1,0,1]
	v_pk_fma_f32 v[20:21], v[86:87], v[74:75], v[20:21] op_sel_hi:[1,0,1]
	s_waitcnt vmcnt(10)
	v_pk_fma_f32 v[24:25], v[88:89], v[50:51], v[24:25] op_sel:[0,1,0]
	v_pk_fma_f32 v[26:27], v[88:89], v[58:59], v[26:27] op_sel:[0,1,0]
	v_pk_fma_f32 v[22:23], v[88:89], v[66:67], v[22:23] op_sel:[0,1,0]
	v_pk_fma_f32 v[20:21], v[88:89], v[74:75], v[20:21] op_sel:[0,1,0]
	s_waitcnt vmcnt(9)
	v_pk_fma_f32 v[24:25], v[90:91], v[52:53], v[24:25] op_sel_hi:[1,0,1]
	v_pk_fma_f32 v[26:27], v[90:91], v[60:61], v[26:27] op_sel_hi:[1,0,1]
	v_pk_fma_f32 v[22:23], v[90:91], v[68:69], v[22:23] op_sel_hi:[1,0,1]
	v_pk_fma_f32 v[20:21], v[90:91], v[76:77], v[20:21] op_sel_hi:[1,0,1]
	s_waitcnt vmcnt(8)
	v_pk_fma_f32 v[24:25], v[92:93], v[100:101], v[24:25] op_sel_hi:[1,0,1]
	v_pk_fma_f32 v[26:27], v[92:93], v[102:103], v[26:27] op_sel_hi:[1,0,1]
	v_pk_fma_f32 v[22:23], v[92:93], v[104:105], v[22:23] op_sel_hi:[1,0,1]
	v_pk_fma_f32 v[20:21], v[92:93], v[106:107], v[20:21] op_sel_hi:[1,0,1]
	s_add_i32 s10, s10, 32
	v_mov_b32_e32 v0, s10
	ds_read_b128 v[28:31], v0
	ds_read_b128 v[50:53], v0 offset:16
	ds_read_b128 v[54:57], v0 offset:16384
	ds_read_b128 v[58:61], v0 offset:16400
	ds_read_b128 v[62:65], v0 offset:32768
	ds_read_b128 v[66:69], v0 offset:32784
	ds_read_b128 v[70:73], v0 offset:49152
	ds_read_b128 v[74:77], v0 offset:49168
	s_waitcnt lgkmcnt(7)
	v_mov_b32_e32 v0, v31
	s_waitcnt lgkmcnt(5)
	v_mov_b32_e32 v94, v57
	s_waitcnt lgkmcnt(3)
	v_mov_b32_e32 v96, v65
	s_waitcnt lgkmcnt(1)
	v_mov_b32_e32 v98, v73
	v_mov_b32_e32 v100, v53
	v_mov_b32_e32 v102, v61
	v_mov_b32_e32 v104, v69
	s_waitcnt lgkmcnt(0)
	v_mov_b32_e32 v106, v77
	s_waitcnt vmcnt(7)
	v_pk_fma_f32 v[24:25], v[108:109], v[28:29], v[24:25] op_sel_hi:[1,0,1]
	v_pk_fma_f32 v[26:27], v[108:109], v[54:55], v[26:27] op_sel_hi:[1,0,1]
	v_pk_fma_f32 v[22:23], v[108:109], v[62:63], v[22:23] op_sel_hi:[1,0,1]
	v_pk_fma_f32 v[20:21], v[108:109], v[70:71], v[20:21] op_sel_hi:[1,0,1]
	s_waitcnt vmcnt(6)
	v_pk_fma_f32 v[24:25], v[110:111], v[28:29], v[24:25] op_sel:[0,1,0]
	v_pk_fma_f32 v[26:27], v[110:111], v[54:55], v[26:27] op_sel:[0,1,0]
	v_pk_fma_f32 v[22:23], v[110:111], v[62:63], v[22:23] op_sel:[0,1,0]
	v_pk_fma_f32 v[20:21], v[110:111], v[70:71], v[20:21] op_sel:[0,1,0]
	s_waitcnt vmcnt(5)
	v_pk_fma_f32 v[24:25], v[112:113], v[30:31], v[24:25] op_sel_hi:[1,0,1]
	v_pk_fma_f32 v[26:27], v[112:113], v[56:57], v[26:27] op_sel_hi:[1,0,1]
	v_pk_fma_f32 v[22:23], v[112:113], v[64:65], v[22:23] op_sel_hi:[1,0,1]
	v_pk_fma_f32 v[20:21], v[112:113], v[72:73], v[20:21] op_sel_hi:[1,0,1]
	s_waitcnt vmcnt(4)
	v_pk_fma_f32 v[24:25], v[114:115], v[0:1], v[24:25] op_sel_hi:[1,0,1]
	v_pk_fma_f32 v[26:27], v[114:115], v[94:95], v[26:27] op_sel_hi:[1,0,1]
	v_pk_fma_f32 v[22:23], v[114:115], v[96:97], v[22:23] op_sel_hi:[1,0,1]
	v_pk_fma_f32 v[20:21], v[114:115], v[98:99], v[20:21] op_sel_hi:[1,0,1]
	s_waitcnt vmcnt(3)
	v_pk_fma_f32 v[24:25], v[116:117], v[50:51], v[24:25] op_sel_hi:[1,0,1]
	v_pk_fma_f32 v[26:27], v[116:117], v[58:59], v[26:27] op_sel_hi:[1,0,1]
	v_pk_fma_f32 v[22:23], v[116:117], v[66:67], v[22:23] op_sel_hi:[1,0,1]
	v_pk_fma_f32 v[20:21], v[116:117], v[74:75], v[20:21] op_sel_hi:[1,0,1]
	s_waitcnt vmcnt(2)
	v_pk_fma_f32 v[24:25], v[118:119], v[50:51], v[24:25] op_sel:[0,1,0]
	v_pk_fma_f32 v[26:27], v[118:119], v[58:59], v[26:27] op_sel:[0,1,0]
	v_pk_fma_f32 v[22:23], v[118:119], v[66:67], v[22:23] op_sel:[0,1,0]
	v_pk_fma_f32 v[20:21], v[118:119], v[74:75], v[20:21] op_sel:[0,1,0]
	s_waitcnt vmcnt(1)
	v_pk_fma_f32 v[24:25], v[120:121], v[52:53], v[24:25] op_sel_hi:[1,0,1]
	v_pk_fma_f32 v[26:27], v[120:121], v[60:61], v[26:27] op_sel_hi:[1,0,1]
	v_pk_fma_f32 v[22:23], v[120:121], v[68:69], v[22:23] op_sel_hi:[1,0,1]
	v_pk_fma_f32 v[20:21], v[120:121], v[76:77], v[20:21] op_sel_hi:[1,0,1]
	s_waitcnt vmcnt(0)
	v_pk_fma_f32 v[24:25], v[122:123], v[100:101], v[24:25] op_sel_hi:[1,0,1]
	v_pk_fma_f32 v[26:27], v[122:123], v[102:103], v[26:27] op_sel_hi:[1,0,1]
	v_pk_fma_f32 v[22:23], v[122:123], v[104:105], v[22:23] op_sel_hi:[1,0,1]
	v_pk_fma_f32 v[20:21], v[122:123], v[106:107], v[20:21] op_sel_hi:[1,0,1]
	s_add_i32 s10, s10, 32
	v_lshl_add_u64 v[16:17], v[16:17], 2, s[8:9]
	v_mad_i64_i32 v[16:17], s[6:7], s4, v49, v[16:17]
	v_add_co_u32_e32 v18, vcc, 0xc000, v16
	global_store_dwordx2 v[16:17], v[24:25], off
	s_nop 0
	v_addc_co_u32_e32 v19, vcc, 0, v17, vcc
	global_store_dwordx2 v[18:19], v[26:27], off
	v_add_co_u32_e32 v18, vcc, 0x18000, v16
	s_nop 1
	v_addc_co_u32_e32 v19, vcc, 0, v17, vcc
	v_add_co_u32_e32 v16, vcc, 0x24000, v16
	global_store_dwordx2 v[18:19], v[22:23], off
	s_nop 0
	v_addc_co_u32_e32 v17, vcc, 0, v17, vcc
	global_store_dwordx2 v[16:17], v[20:21], off
	s_branch .LBB0_22

.LBB0_1177:
	v_add_u32_e32 v36, v237, v230
	v_add_u32_e32 v37, v237, v231
	v_add_u32_e32 v38, v237, v232
	v_add_u32_e32 v39, v237, v233
	ds_read_b128 v[32:35], v236 offset:8192
	ds_read_b128 v[64:67], v238 offset:8192
	ds_read_b128 v[68:71], v239 offset:8192
	ds_read_b128 v[72:75], v240 offset:8192
	ds_read_b128 v[236:239], v36
	ds_read_b128 v[76:79], v36 offset:8192
	ds_read_b128 v[240:243], v37
	ds_read_b128 v[80:83], v37 offset:8192
	ds_read_b128 v[244:247], v38
	ds_read_b128 v[84:87], v38 offset:8192
	ds_read_b128 v[248:251], v39
	ds_read_b128 v[88:91], v39 offset:8192
	s_setprio 1
	s_waitcnt lgkmcnt(11)
	v_mfma_f32_32x32x16_f16 v[48:63], v[128:131], v[32:35], 0
	v_mfma_f32_32x32x16_f16 v[32:47], v[136:139], v[32:35], 0
	s_waitcnt lgkmcnt(10)
	v_mfma_f32_32x32x16_f16 v[48:63], v[132:135], v[64:67], v[48:63]
	v_mfma_f32_32x32x16_f16 v[32:47], v[140:143], v[64:67], v[32:47]
	s_waitcnt lgkmcnt(9)
	v_mfma_f32_32x32x16_f16 v[48:63], v[144:147], v[68:71], v[48:63]
	v_mfma_f32_32x32x16_f16 v[32:47], v[152:155], v[68:71], v[32:47]
	s_waitcnt lgkmcnt(8)
	v_mfma_f32_32x32x16_f16 v[48:63], v[148:151], v[72:75], v[48:63]
	v_mfma_f32_32x32x16_f16 v[32:47], v[156:159], v[72:75], v[32:47]
	s_waitcnt lgkmcnt(6)
	v_mfma_f32_32x32x16_f16 v[48:63], v[160:163], v[76:79], v[48:63]
	v_mfma_f32_32x32x16_f16 v[32:47], v[168:171], v[76:79], v[32:47]
	s_waitcnt lgkmcnt(4)
	v_mfma_f32_32x32x16_f16 v[48:63], v[164:167], v[80:83], v[48:63]
	v_mfma_f32_32x32x16_f16 v[32:47], v[172:175], v[80:83], v[32:47]
	s_waitcnt lgkmcnt(2)
	v_mfma_f32_32x32x16_f16 v[48:63], v[176:179], v[84:87], v[48:63]
	v_mfma_f32_32x32x16_f16 v[32:47], v[184:187], v[84:87], v[32:47]
	s_waitcnt lgkmcnt(0)
	v_mfma_f32_32x32x16_f16 v[48:63], v[180:183], v[88:91], v[48:63]
	v_mfma_f32_32x32x16_f16 v[32:47], v[188:191], v[88:91], v[32:47]
	v_mfma_f32_32x32x16_f16 v[80:95], v[128:131], v[204:207], 0
	v_mfma_f32_32x32x16_f16 v[64:79], v[136:139], v[204:207], 0
	v_mfma_f32_32x32x16_f16 v[80:95], v[132:135], v[196:199], v[80:95]
	v_mfma_f32_32x32x16_f16 v[64:79], v[140:143], v[196:199], v[64:79]
	v_mfma_f32_32x32x16_f16 v[80:95], v[144:147], v[200:203], v[80:95]
	v_mfma_f32_32x32x16_f16 v[64:79], v[152:155], v[200:203], v[64:79]
	v_mfma_f32_32x32x16_f16 v[80:95], v[148:151], v[192:195], v[80:95]
	v_mfma_f32_32x32x16_f16 v[64:79], v[156:159], v[192:195], v[64:79]
	v_mfma_f32_32x32x16_f16 v[80:95], v[160:163], v[236:239], v[80:95]
	v_mfma_f32_32x32x16_f16 v[64:79], v[168:171], v[236:239], v[64:79]
	v_mfma_f32_32x32x16_f16 v[80:95], v[164:167], v[240:243], v[80:95]
	v_mfma_f32_32x32x16_f16 v[64:79], v[172:175], v[240:243], v[64:79]
	v_mfma_f32_32x32x16_f16 v[80:95], v[176:179], v[244:247], v[80:95]
	v_mfma_f32_32x32x16_f16 v[64:79], v[184:187], v[244:247], v[64:79]
	v_mfma_f32_32x32x16_f16 v[80:95], v[180:183], v[248:251], v[80:95]
	v_mfma_f32_32x32x16_f16 v[64:79], v[188:191], v[248:251], v[64:79]
	s_setprio 0
	s_andn2_b64 vcc, exec, s[86:87]
	s_cbranch_vccz .LBB0_1163
	s_mov_b32 s92, s96
	s_branch .LBB0_1164
